# P1 late weight copy (W_out, gate/up) rewritten: LDS-free dwordx4 transpose, 2 items in flight per wave
# speedup vs baseline: 1.0147x; 1.0147x over previous
; __device__ __forceinline__ void p0_transpose_item(const float* W, int K, int N, bf16* WT, const float* gain, int mode, LAS float* scr, int item, int lane) {
;     const int nblk = N / 32, kb = item / nblk, nb = item % nblk, k0 = 64 * kb, n0 = 32 * nb;
; #pragma unroll 8
;     for (int i = 0; i < 32; ++i) { const int kk = 2 * i + (lane >> 5); scr[kk * 33 + (lane & 31)] = __builtin_nontemporal_load(W + (size_t)(k0 + kk) * N + n0 + (lane & 31)); }
;     LDS_WAIT(); asm volatile("" ::: "memory");
;     const int c = lane & 7;
;     float g[8];
; #pragma unroll
;     for (int i = 0; i < 8; ++i) g[i] = gain ? gain[k0 + 8 * c + i] : 1.0f;
;     const int rbase = (mode == 0) ? n0 : (256 * (n0 >> 7) + (n0 & 127) + (mode == 2 ? 128 : 0));
; #pragma unroll
;     for (int j = 0; j < 4; ++j) { const int n = (lane >> 3) + 8 * j; const LAS float* s = scr + (8 * c) * 33 + n;
;         v4u o; o.x = pk2(s[0 * 33] * g[0], s[1 * 33] * g[1]); o.y = pk2(s[2 * 33] * g[2], s[3 * 33] * g[3]); o.z = pk2(s[4 * 33] * g[4], s[5 * 33] * g[5]); o.w = pk2(s[6 * 33] * g[6], s[7 * 33] * g[7]);
;         *(GAS v4u*)(WT + (size_t)(rbase + n) * K + k0 + 8 * c) = o; }
;     LDS_WAIT(); asm volatile("" ::: "memory");
; }
; __device__ __forceinline__ void p0_weights_late(Frame& F, int first_block, int which) {
;     int wv = threadIdx.x >> 6, ln = threadIdx.x & 63;
;     asm volatile("" : "+v"(wv), "+v"(ln));
;     wv = __builtin_amdgcn_readfirstlane(wv);
;     LAS float* scr = (LAS float*)(F.lds + wv * 16384);
;     const int gw = (blockIdx.x - first_block) * NWAVES + wv, NGW = (F.G - first_block) * NWAVES;
;     constexpr int I_OUT = (D / 64) * (D / 32), I_G = (D / 64) * (FF / 32), I_DN = (FF / 64) * (D / 32);
;     if (which == 0) {
;         for (int it = gw; it < I_OUT + 2 * I_G; it += NGW) {
;             int r = it;
;             if (r < I_OUT) { p0_transpose_item(F.w_out, D, D, F.WOUT, nullptr, 0, scr, r, ln); continue; } r -= I_OUT;
;             if (r < I_G) { p0_transpose_item(F.w_gate, D, FF, F.WGU, F.g2, 1, scr, r, ln); continue; } r -= I_G;
;             p0_transpose_item(F.w_up, D, FF, F.WGU, F.g2, 2, scr, r, ln);
;         }
; template <bool COOP>
; __global__ void __launch_bounds__(NWAVES * 64, 2) fwd(Args args) {
;     ...
;             const int nwg = (M / 256) * (PW / 256), rem = nwg % F.G;
;             const int first_late = (rem == 0) ? 0 : rem;
.LBB0_345:
	s_abs_i32 s0, s3
	v_cvt_f32_u32_e32 v1, s0
	s_sub_i32 s1, 0, s0
	v_rcp_iflag_f32_e32 v1, v1
	s_nop 0
	v_mul_f32_e32 v1, 0x4f7ffffe, v1
	v_cvt_u32_f32_e32 v1, v1
	s_nop 0
	v_readfirstlane_b32 s4, v1
	s_mul_i32 s1, s1, s4
	s_mul_hi_u32 s1, s4, s1
	s_add_i32 s4, s4, s1
	s_mul_hi_u32 s1, s4, 0x2c0
	s_mul_i32 s1, s1, s0
	s_sub_i32 s1, 0x2c0, s1
	s_sub_i32 s4, s1, s0
	s_cmp_ge_u32 s1, s0
	s_cselect_b32 s1, s4, s1
	s_sub_i32 s4, s1, s0
	s_cmp_ge_u32 s1, s0
	s_cselect_b32 s0, s4, s1
	s_cmp_lt_i32 s2, s0
	s_cbranch_scc1 .LBB0_395
	v_lshrrev_b32_e32 v1, 6, v0
	v_mov_b32_e32 v3, v206
	s_sub_i32 s4, s2, s0
	s_barrier
	s_lshl_b32 s4, s4, 3
	v_readfirstlane_b32 s1, v1
	s_add_i32 s20, s1, s4
	s_cmpk_gt_i32 s20, 0xcff
	s_cbranch_scc1 .LBB0_395
	s_sub_i32 s0, s3, s0
	s_lshl_b32 s21, s0, 3
	v_lshrrev_b32_e32 v94, 3, v206
	v_and_b32_e32 v95, 7, v206
	v_lshlrev_b32_e32 v108, 5, v94
	s_mul_i32 s73, s21, 1
	v_mul_u32_u24_e32 v96, 0x8000, v94
	v_lshl_add_u32 v96, v95, 4, v96
	v_add_u32_e32 v97, 0x1000, v96
	v_add_u32_e32 v98, 0x2000, v96
	v_add_u32_e32 v99, 0x3000, v96
	v_add_u32_e32 v100, 0x4000, v96
	v_add_u32_e32 v101, 0x5000, v96
	v_add_u32_e32 v102, 0x6000, v96
	v_add_u32_e32 v103, 0x7000, v96
	v_mul_u32_u24_e32 v104, 0x2000, v95
	v_lshl_add_u32 v104, v94, 4, v104
	v_add_u32_e32 v105, 0x800, v104
	v_add_u32_e32 v106, 0x1000, v104
	v_add_u32_e32 v107, 0x1800, v104
	s_add_u32 s86, s58, 0x800000
	s_addc_u32 s87, s59, 0
	s_mov_b32 s66, s20
	s_cmp_lt_i32 s66, 512
	s_cbranch_scc0 .Lht_l0_0_done
.Lht_l0_0_loop:
	s_mov_b32 s67, s66
	s_mov_b32 s74, s12
	s_mov_b32 s75, s13
	s_mul_hi_u32 s68, s67, 0x8000000
	s_mul_i32 s70, s68, 32
	s_sub_i32 s69, s67, s70
	s_mul_i32 s70, s68, 0x40000
	s_lshl_b32 s71, s69, 7
	s_add_i32 s70, s70, s71
	s_add_u32 s74, s74, s70
	s_addc_u32 s75, s75, 0
	s_lshl_b32 s70, s69, 5
	s_mul_i32 s70, s70, 0x800
	s_lshl_b32 s71, s68, 7
	s_add_i32 s70, s70, s71
	s_add_u32 s78, s86, s70
	s_addc_u32 s79, s87, 0
	global_load_dwordx4 v[110:113], v96, s[74:75] nt
	global_load_dwordx4 v[114:117], v97, s[74:75] nt
	global_load_dwordx4 v[118:121], v98, s[74:75] nt
	global_load_dwordx4 v[122:125], v99, s[74:75] nt
	global_load_dwordx4 v[126:129], v100, s[74:75] nt
	global_load_dwordx4 v[130:133], v101, s[74:75] nt
	global_load_dwordx4 v[134:137], v102, s[74:75] nt
	global_load_dwordx4 v[138:141], v103, s[74:75] nt
	s_add_i32 s67, s66, s73
	s_cmp_lt_i32 s67, 512
	s_cbranch_scc0 .Lht_l0_0_ld1_skip
	s_mov_b32 s76, s12
	s_mov_b32 s77, s13
	s_mul_hi_u32 s68, s67, 0x8000000
	s_mul_i32 s70, s68, 32
	s_sub_i32 s69, s67, s70
	s_mul_i32 s70, s68, 0x40000
	s_lshl_b32 s71, s69, 7
	s_add_i32 s70, s70, s71
	s_add_u32 s76, s76, s70
	s_addc_u32 s77, s77, 0
	s_lshl_b32 s70, s69, 5
	s_mul_i32 s70, s70, 0x800
	s_lshl_b32 s71, s68, 7
	s_add_i32 s70, s70, s71
	s_add_u32 s80, s86, s70
	s_addc_u32 s81, s87, 0
	global_load_dwordx4 v[142:145], v96, s[76:77] nt
	global_load_dwordx4 v[146:149], v97, s[76:77] nt
	global_load_dwordx4 v[150:153], v98, s[76:77] nt
	global_load_dwordx4 v[154:157], v99, s[76:77] nt
	global_load_dwordx4 v[158:161], v100, s[76:77] nt
	global_load_dwordx4 v[162:165], v101, s[76:77] nt
	global_load_dwordx4 v[166:169], v102, s[76:77] nt
	global_load_dwordx4 v[170:173], v103, s[76:77] nt
.Lht_l0_0_ld1_skip:
	s_waitcnt vmcnt(0)
	v_cvt_pk_bf16_f32 v190, v110, v114
	v_cvt_pk_bf16_f32 v191, v118, v122
	v_cvt_pk_bf16_f32 v192, v126, v130
	v_cvt_pk_bf16_f32 v193, v134, v138
	v_cvt_pk_bf16_f32 v194, v111, v115
	v_cvt_pk_bf16_f32 v195, v119, v123
	v_cvt_pk_bf16_f32 v196, v127, v131
	v_cvt_pk_bf16_f32 v197, v135, v139
	v_cvt_pk_bf16_f32 v198, v112, v116
	v_cvt_pk_bf16_f32 v199, v120, v124
	v_cvt_pk_bf16_f32 v200, v128, v132
	v_cvt_pk_bf16_f32 v201, v136, v140
	v_cvt_pk_bf16_f32 v202, v113, v117
	v_cvt_pk_bf16_f32 v203, v121, v125
	v_cvt_pk_bf16_f32 v204, v129, v133
	v_cvt_pk_bf16_f32 v205, v137, v141
	global_store_dwordx4 v104, v[190:193], s[78:79]
	global_store_dwordx4 v105, v[194:197], s[78:79]
	global_store_dwordx4 v106, v[198:201], s[78:79]
	global_store_dwordx4 v107, v[202:205], s[78:79]
	s_add_i32 s67, s66, s73
	s_cmp_lt_i32 s67, 512
	s_cbranch_scc0 .Lht_l0_0_st1_skip
	v_cvt_pk_bf16_f32 v208, v142, v146
	v_cvt_pk_bf16_f32 v209, v150, v154
	v_cvt_pk_bf16_f32 v210, v158, v162
	v_cvt_pk_bf16_f32 v211, v166, v170
	v_cvt_pk_bf16_f32 v212, v143, v147
	v_cvt_pk_bf16_f32 v213, v151, v155
	v_cvt_pk_bf16_f32 v214, v159, v163
	v_cvt_pk_bf16_f32 v215, v167, v171
	v_cvt_pk_bf16_f32 v216, v144, v148
	v_cvt_pk_bf16_f32 v217, v152, v156
	v_cvt_pk_bf16_f32 v218, v160, v164
	v_cvt_pk_bf16_f32 v219, v168, v172
	v_cvt_pk_bf16_f32 v220, v145, v149
	v_cvt_pk_bf16_f32 v221, v153, v157
	v_cvt_pk_bf16_f32 v222, v161, v165
	v_cvt_pk_bf16_f32 v223, v169, v173
	global_store_dwordx4 v104, v[208:211], s[80:81]
	global_store_dwordx4 v105, v[212:215], s[80:81]
	global_store_dwordx4 v106, v[216:219], s[80:81]
	global_store_dwordx4 v107, v[220:223], s[80:81]
.Lht_l0_0_st1_skip:
	s_mul_i32 s67, s21, 2
	s_add_i32 s66, s66, s67
	s_cmp_lt_i32 s66, 512
	s_cbranch_scc1 .Lht_l0_0_loop
.Lht_l0_0_done:
	v_mul_u32_u24_e32 v96, 0x16000, v94
	v_lshl_add_u32 v96, v95, 4, v96
	v_add_u32_e32 v97, 0x2c00, v96
	v_add_u32_e32 v98, 0x5800, v96
	v_add_u32_e32 v99, 0x8400, v96
	v_add_u32_e32 v100, 0xb000, v96
	v_add_u32_e32 v101, 0xdc00, v96
	v_add_u32_e32 v102, 0x10800, v96
	v_add_u32_e32 v103, 0x13400, v96
	v_mul_u32_u24_e32 v104, 0x2000, v95
	v_lshl_add_u32 v104, v94, 4, v104
	v_add_u32_e32 v105, 0x800, v104
	v_add_u32_e32 v106, 0x1000, v104
	v_add_u32_e32 v107, 0x1800, v104
	s_add_u32 s86, s58, 0xa00000
	s_addc_u32 s87, s59, 0
	s_mov_b32 s66, s20
	s_cmp_lt_i32 s66, 2816
	s_cbranch_scc0 .Lht_l0_1_done
; #define GAS __attribute__((address_space(1)))
; #define LAS __attribute__((address_space(3)))
; #define LDS_WAIT() asm volatile("s_waitcnt lgkmcnt(0)" ::: "memory")
; __device__ __forceinline__ unsigned pk2(float lo, float hi) { return f2bf(lo) | (f2bf(hi) << 16); }
; __device__ __forceinline__ void p0_transpose_item(const float* W, int K, int N, bf16* WT, const float* gain, int mode, LAS float* scr, int item, int lane) {
;     const int nblk = N / 32, kb = item / nblk, nb = item % nblk, k0 = 64 * kb, n0 = 32 * nb;
; #pragma unroll 8
;     for (int i = 0; i < 32; ++i) { const int kk = 2 * i + (lane >> 5); scr[kk * 33 + (lane & 31)] = __builtin_nontemporal_load(W + (size_t)(k0 + kk) * N + n0 + (lane & 31)); }
;     LDS_WAIT(); asm volatile("" ::: "memory");
;     const int c = lane & 7;
;     float g[8];
; #pragma unroll
;     for (int i = 0; i < 8; ++i) g[i] = gain ? gain[k0 + 8 * c + i] : 1.0f;
;     const int rbase = (mode == 0) ? n0 : (256 * (n0 >> 7) + (n0 & 127) + (mode == 2 ? 128 : 0));
; #pragma unroll
;     for (int j = 0; j < 4; ++j) { const int n = (lane >> 3) + 8 * j; const LAS float* s = scr + (8 * c) * 33 + n;
;         v4u o; o.x = pk2(s[0 * 33] * g[0], s[1 * 33] * g[1]); o.y = pk2(s[2 * 33] * g[2], s[3 * 33] * g[3]); o.z = pk2(s[4 * 33] * g[4], s[5 * 33] * g[5]); o.w = pk2(s[6 * 33] * g[6], s[7 * 33] * g[7]);
;         *(GAS v4u*)(WT + (size_t)(rbase + n) * K + k0 + 8 * c) = o; }
; __device__ __forceinline__ void p0_weights_late(Frame& F, int first_block, int which) {
;     ...
;             if (r < I_G) { p0_transpose_item(F.w_gate, D, FF, F.WGU, F.g2, 1, scr, r, ln); continue; } r -= I_G;
;             p0_transpose_item(F.w_up, D, FF, F.WGU, F.g2, 2, scr, r, ln);
.Lht_l0_1_loop:
	s_mov_b32 s67, s66
	s_cmp_ge_i32 s67, 1408
	s_cselect_b32 s72, 1, 0
	s_cselect_b32 s70, 1408, 0
	s_sub_i32 s67, s67, s70
	s_cmp_lg_u32 s72, 0
	s_cselect_b32 s74, s18, s16
	s_cselect_b32 s75, s19, s17
	s_mul_hi_u32 s68, s67, 0x2e8ba2f
	s_mul_i32 s70, s68, 88
	s_sub_i32 s69, s67, s70
	s_mul_i32 s70, s68, 0xb0000
	s_lshl_b32 s71, s69, 7
	s_add_i32 s70, s70, s71
	s_add_u32 s74, s74, s70
	s_addc_u32 s75, s75, 0
	s_lshr_b32 s70, s69, 2
	s_lshl_b32 s70, s70, 8
	s_and_b32 s71, s69, 3
	s_lshl_b32 s71, s71, 5
	s_add_i32 s70, s70, s71
	s_lshl_b32 s71, s72, 7
	s_add_i32 s70, s70, s71
	s_mul_i32 s70, s70, 0x800
	s_lshl_b32 s71, s68, 7
	s_add_i32 s70, s70, s71
	s_add_u32 s78, s86, s70
	s_addc_u32 s79, s87, 0
	s_lshl_b32 s70, s68, 8
	s_add_u32 s82, s14, s70
	s_addc_u32 s83, s15, 0
	global_load_dwordx4 v[110:113], v96, s[74:75] nt
	global_load_dwordx4 v[114:117], v97, s[74:75] nt
	global_load_dwordx4 v[118:121], v98, s[74:75] nt
	global_load_dwordx4 v[122:125], v99, s[74:75] nt
	global_load_dwordx4 v[126:129], v100, s[74:75] nt
	global_load_dwordx4 v[130:133], v101, s[74:75] nt
	global_load_dwordx4 v[134:137], v102, s[74:75] nt
	global_load_dwordx4 v[138:141], v103, s[74:75] nt
	global_load_dwordx4 v[174:177], v108, s[82:83]
	global_load_dwordx4 v[178:181], v108, s[82:83] offset:16
	s_add_i32 s67, s66, s73
	s_cmp_lt_i32 s67, 2816
	s_cbranch_scc0 .Lht_l0_1_ld1_skip
	s_cmp_ge_i32 s67, 1408
	s_cselect_b32 s72, 1, 0
	s_cselect_b32 s70, 1408, 0
	s_sub_i32 s67, s67, s70
	s_cmp_lg_u32 s72, 0
	s_cselect_b32 s76, s18, s16
	s_cselect_b32 s77, s19, s17
	s_mul_hi_u32 s68, s67, 0x2e8ba2f
	s_mul_i32 s70, s68, 88
	s_sub_i32 s69, s67, s70
	s_mul_i32 s70, s68, 0xb0000
	s_lshl_b32 s71, s69, 7
	s_add_i32 s70, s70, s71
	s_add_u32 s76, s76, s70
	s_addc_u32 s77, s77, 0
	s_lshr_b32 s70, s69, 2
	s_lshl_b32 s70, s70, 8
	s_and_b32 s71, s69, 3
	s_lshl_b32 s71, s71, 5
	s_add_i32 s70, s70, s71
	s_lshl_b32 s71, s72, 7
	s_add_i32 s70, s70, s71
	s_mul_i32 s70, s70, 0x800
	s_lshl_b32 s71, s68, 7
	s_add_i32 s70, s70, s71
	s_add_u32 s80, s86, s70
	s_addc_u32 s81, s87, 0
	s_lshl_b32 s70, s68, 8
	s_add_u32 s84, s14, s70
	s_addc_u32 s85, s15, 0
	global_load_dwordx4 v[142:145], v96, s[76:77] nt
	global_load_dwordx4 v[146:149], v97, s[76:77] nt
	global_load_dwordx4 v[150:153], v98, s[76:77] nt
	global_load_dwordx4 v[154:157], v99, s[76:77] nt
	global_load_dwordx4 v[158:161], v100, s[76:77] nt
	global_load_dwordx4 v[162:165], v101, s[76:77] nt
	global_load_dwordx4 v[166:169], v102, s[76:77] nt
	global_load_dwordx4 v[170:173], v103, s[76:77] nt
	global_load_dwordx4 v[182:185], v108, s[84:85]
	global_load_dwordx4 v[186:189], v108, s[84:85] offset:16
; #define GAS __attribute__((address_space(1)))
; #define LAS __attribute__((address_space(3)))
; __device__ __forceinline__ unsigned pk2(float lo, float hi) { return f2bf(lo) | (f2bf(hi) << 16); }
; __device__ __forceinline__ void p0_transpose_item(const float* W, int K, int N, bf16* WT, const float* gain, int mode, LAS float* scr, int item, int lane) {
;     ...
; #pragma unroll
;     for (int i = 0; i < 8; ++i) g[i] = gain ? gain[k0 + 8 * c + i] : 1.0f;
;     const int rbase = (mode == 0) ? n0 : (256 * (n0 >> 7) + (n0 & 127) + (mode == 2 ? 128 : 0));
; #pragma unroll
;     for (int j = 0; j < 4; ++j) { const int n = (lane >> 3) + 8 * j; const LAS float* s = scr + (8 * c) * 33 + n;
;         v4u o; o.x = pk2(s[0 * 33] * g[0], s[1 * 33] * g[1]); o.y = pk2(s[2 * 33] * g[2], s[3 * 33] * g[3]); o.z = pk2(s[4 * 33] * g[4], s[5 * 33] * g[5]); o.w = pk2(s[6 * 33] * g[6], s[7 * 33] * g[7]);
;         *(GAS v4u*)(WT + (size_t)(rbase + n) * K + k0 + 8 * c) = o; }
; __device__ __forceinline__ void xcd_barrier(const XcdBarrier& b) {
;     asm volatile("s_waitcnt vmcnt(0)" ::: "memory");
;     __syncthreads();
;     if (threadIdx.x == 0) {
;         unsigned* bar = b.bar;
;         __builtin_amdgcn_s_waitcnt(0);
;         unsigned nloc = b.st[0], nx = b.st[1];
;         if (nloc == 0u) { xcd_barrier_complete(bar, b.x, nloc, nx); b.st[0] = nloc; b.st[1] = nx; }
.Lht_l0_1_ld1_skip:
	s_waitcnt vmcnt(0)
	v_mul_f32_e32 v110, v110, v174
	v_mul_f32_e32 v111, v111, v174
	v_mul_f32_e32 v112, v112, v174
	v_mul_f32_e32 v113, v113, v174
	v_mul_f32_e32 v114, v114, v175
	v_mul_f32_e32 v115, v115, v175
	v_mul_f32_e32 v116, v116, v175
	v_mul_f32_e32 v117, v117, v175
	v_mul_f32_e32 v118, v118, v176
	v_mul_f32_e32 v119, v119, v176
	v_mul_f32_e32 v120, v120, v176
	v_mul_f32_e32 v121, v121, v176
	v_mul_f32_e32 v122, v122, v177
	v_mul_f32_e32 v123, v123, v177
	v_mul_f32_e32 v124, v124, v177
	v_mul_f32_e32 v125, v125, v177
	v_mul_f32_e32 v126, v126, v178
	v_mul_f32_e32 v127, v127, v178
	v_mul_f32_e32 v128, v128, v178
	v_mul_f32_e32 v129, v129, v178
	v_mul_f32_e32 v130, v130, v179
	v_mul_f32_e32 v131, v131, v179
	v_mul_f32_e32 v132, v132, v179
	v_mul_f32_e32 v133, v133, v179
	v_mul_f32_e32 v134, v134, v180
	v_mul_f32_e32 v135, v135, v180
	v_mul_f32_e32 v136, v136, v180
	v_mul_f32_e32 v137, v137, v180
	v_mul_f32_e32 v138, v138, v181
	v_mul_f32_e32 v139, v139, v181
	v_mul_f32_e32 v140, v140, v181
	v_mul_f32_e32 v141, v141, v181
	v_cvt_pk_bf16_f32 v190, v110, v114
	v_cvt_pk_bf16_f32 v191, v118, v122
	v_cvt_pk_bf16_f32 v192, v126, v130
	v_cvt_pk_bf16_f32 v193, v134, v138
	v_cvt_pk_bf16_f32 v194, v111, v115
	v_cvt_pk_bf16_f32 v195, v119, v123
	v_cvt_pk_bf16_f32 v196, v127, v131
	v_cvt_pk_bf16_f32 v197, v135, v139
	v_cvt_pk_bf16_f32 v198, v112, v116
	v_cvt_pk_bf16_f32 v199, v120, v124
	v_cvt_pk_bf16_f32 v200, v128, v132
	v_cvt_pk_bf16_f32 v201, v136, v140
	v_cvt_pk_bf16_f32 v202, v113, v117
	v_cvt_pk_bf16_f32 v203, v121, v125
	v_cvt_pk_bf16_f32 v204, v129, v133
	v_cvt_pk_bf16_f32 v205, v137, v141
	global_store_dwordx4 v104, v[190:193], s[78:79]
	global_store_dwordx4 v105, v[194:197], s[78:79]
	global_store_dwordx4 v106, v[198:201], s[78:79]
	global_store_dwordx4 v107, v[202:205], s[78:79]
	s_add_i32 s67, s66, s73
	s_cmp_lt_i32 s67, 2816
	s_cbranch_scc0 .Lht_l0_1_st1_skip
	v_mul_f32_e32 v142, v142, v182
	v_mul_f32_e32 v143, v143, v182
	v_mul_f32_e32 v144, v144, v182
	v_mul_f32_e32 v145, v145, v182
	v_mul_f32_e32 v146, v146, v183
	v_mul_f32_e32 v147, v147, v183
	v_mul_f32_e32 v148, v148, v183
	v_mul_f32_e32 v149, v149, v183
	v_mul_f32_e32 v150, v150, v184
	v_mul_f32_e32 v151, v151, v184
	v_mul_f32_e32 v152, v152, v184
	v_mul_f32_e32 v153, v153, v184
	v_mul_f32_e32 v154, v154, v185
	v_mul_f32_e32 v155, v155, v185
	v_mul_f32_e32 v156, v156, v185
	v_mul_f32_e32 v157, v157, v185
	v_mul_f32_e32 v158, v158, v186
	v_mul_f32_e32 v159, v159, v186
	v_mul_f32_e32 v160, v160, v186
	v_mul_f32_e32 v161, v161, v186
	v_mul_f32_e32 v162, v162, v187
	v_mul_f32_e32 v163, v163, v187
	v_mul_f32_e32 v164, v164, v187
	v_mul_f32_e32 v165, v165, v187
	v_mul_f32_e32 v166, v166, v188
	v_mul_f32_e32 v167, v167, v188
	v_mul_f32_e32 v168, v168, v188
	v_mul_f32_e32 v169, v169, v188
	v_mul_f32_e32 v170, v170, v189
	v_mul_f32_e32 v171, v171, v189
	v_mul_f32_e32 v172, v172, v189
	v_mul_f32_e32 v173, v173, v189
	v_cvt_pk_bf16_f32 v208, v142, v146
	v_cvt_pk_bf16_f32 v209, v150, v154
	v_cvt_pk_bf16_f32 v210, v158, v162
	v_cvt_pk_bf16_f32 v211, v166, v170
	v_cvt_pk_bf16_f32 v212, v143, v147
	v_cvt_pk_bf16_f32 v213, v151, v155
	v_cvt_pk_bf16_f32 v214, v159, v163
	v_cvt_pk_bf16_f32 v215, v167, v171
	v_cvt_pk_bf16_f32 v216, v144, v148
	v_cvt_pk_bf16_f32 v217, v152, v156
	v_cvt_pk_bf16_f32 v218, v160, v164
	v_cvt_pk_bf16_f32 v219, v168, v172
	v_cvt_pk_bf16_f32 v220, v145, v149
	v_cvt_pk_bf16_f32 v221, v153, v157
	v_cvt_pk_bf16_f32 v222, v161, v165
	v_cvt_pk_bf16_f32 v223, v169, v173
	global_store_dwordx4 v104, v[208:211], s[80:81]
	global_store_dwordx4 v105, v[212:215], s[80:81]
	global_store_dwordx4 v106, v[216:219], s[80:81]
	global_store_dwordx4 v107, v[220:223], s[80:81]
.Lht_l0_1_st1_skip:
	s_mul_i32 s67, s21, 2
	s_add_i32 s66, s66, s67
	s_cmp_lt_i32 s66, 2816
	s_cbranch_scc1 .Lht_l0_1_loop
.Lht_l0_1_done:
.LBB0_395:
	s_andn2_b64 vcc, exec, s[10:11]
	s_cbranch_vccnz .LBB0_449
	s_waitcnt vmcnt(0)
	s_barrier
	s_and_saveexec_b64 s[0:1], s[28:29]
	s_cbranch_execz .LBB0_448
	s_add_i32 s4, 0, 0x20160
	v_mov_b32_e32 v1, s4
	s_waitcnt vmcnt(0) expcnt(0) lgkmcnt(0)
	ds_read_b32 v3, v1
	s_add_i32 s4, 0, 0x20164
	v_mov_b32_e32 v1, s4
	ds_read_b32 v1, v1
	s_waitcnt lgkmcnt(1)
	v_cmp_ne_u32_e32 vcc, 0, v3
	s_cbranch_vccnz .LBB0_412
	v_readlane_b32 s4, v238, 0
	v_readlane_b32 s5, v238, 1
	s_load_dwordx2 s[8:9], s[4:5], 0x4
	s_add_u32 s4, s58, 0x4200
	s_addc_u32 s5, s59, 0
	s_add_u32 s6, s58, 0x4400
	s_addc_u32 s7, s59, 0
	s_waitcnt lgkmcnt(0)
	s_mul_i32 s30, s8, s3
	s_add_u32 s8, s58, 0x4500
	s_mul_i32 s30, s30, s9
	s_addc_u32 s9, s59, 0
	s_add_u32 s12, s58, 0x4600
	s_addc_u32 s13, s59, 0
	s_add_u32 s14, s58, 0x4700
	s_addc_u32 s15, s59, 0
	s_add_u32 s16, s58, 0x4800
	s_addc_u32 s17, s59, 0
	s_add_u32 s18, s58, 0x4900
	s_addc_u32 s19, s59, 0
	s_add_u32 s20, s58, 0x4a00
	s_addc_u32 s21, s59, 0
	s_add_u32 s22, s58, 0x4b00
	s_addc_u32 s23, s59, 0
	s_add_u32 s24, s58, 0x4c00
	s_addc_u32 s25, s59, 0
	s_add_u32 s26, s58, 0x4d00
	s_addc_u32 s27, s59, 0
	s_add_u32 s42, s58, 0x4e00
	s_addc_u32 s43, s59, 0
	s_add_u32 s68, s58, 0x4f00
	s_addc_u32 s69, s59, 0
	s_add_u32 s70, s58, 0x5000
	s_addc_u32 s71, s59, 0
	s_add_u32 s72, s58, 0x5100
	s_addc_u32 s73, s59, 0
	s_add_u32 s74, s58, 0x5200
	s_addc_u32 s75, s59, 0
	s_add_u32 s76, s58, 0x5300
	s_addc_u32 s77, s59, 0
	s_mov_b32 s31, 1
	v_mov_b32_e32 v17, 0
	s_branch .LBB0_400
